# attention softmax: canonicalizing v_max pairs replaced by v_max3 tree, 0+p0 add folded
# speedup vs baseline: 1.0018x; 1.0018x over previous
; __device__ __forceinline__ unsigned cvt_pk_bf16(float lo, float hi) { const f32x2c_ v = {lo, hi}; const bf16x2c_ b = __builtin_convertvector(v, bf16x2c_); return __builtin_bit_cast(unsigned, b); }
; __device__ __forceinline__ void attn_unit(int bh, int qb, const bf16_t* QKV, const bf16_t* KF, const float* cstab, const float* qg, bf16_t* MIX, LAS unsigned char* lds) {
;     ...
;             float mx = fmaxf(fmaxf(p[0], p[1]), fmaxf(p[2], p[3]));
; #pragma unroll
;             for (int r = 4; r < 16; r += 4) mx = fmaxf(mx, fmaxf(fmaxf(p[r], p[r + 1]), fmaxf(p[r + 2], p[r + 3])));
;             mx = pg8::max32(mx);
;             if (key0 == 0 || __any(mx > 4.0f)) {
;                 const float dl = (key0 == 0) ? mx : fmaxf(mx, 0.f), f = __builtin_amdgcn_exp2f(-dl);
;                 mrun += dl; lrun *= f;
; #pragma unroll
;                 for (int r = 0; r < 16; ++r) { o0[r] *= f; o1[r] *= f; p[r] -= dl; negm[r] = -mrun; }
;             }
;             float ps = 0.f;
; #pragma unroll
;             for (int r = 0; r < 16; ++r) { p[r] = __builtin_amdgcn_exp2f(p[r]); ps += p[r]; }
;             lrun += ps;
;             u32x4 w0, w1;
; #pragma unroll
;             for (int k = 0; k < 4; ++k) { w0[k] = cvt_pk_bf16(p[2 * k], p[2 * k + 1]); w1[k] = cvt_pk_bf16(p[8 + 2 * k], p[8 + 2 * k + 1]); }
;             const bf16x8 pb0 = __builtin_bit_cast(bf16x8, w0), pb1 = __builtin_bit_cast(bf16x8, w1);
;             const LAS unsigned char* vp = buf + vtb + (32 * kb) * VROW;
; #pragma unroll
;             for (int db = 0; db < 2; ++db) {
;                 const v4i16_t a0 = __builtin_amdgcn_ds_read_tr16_b64_v4i16((LAS v4i16_t*)(vp + db * 64));
;                 const v4i16_t a1 = __builtin_amdgcn_ds_read_tr16_b64_v4i16((LAS v4i16_t*)(vp + db * 64 + 8 * VROW));
;                 const v4i16_t c0 = __builtin_amdgcn_ds_read_tr16_b64_v4i16((LAS v4i16_t*)(vp + db * 64 + 16 * VROW));
;                 const v4i16_t c1 = __builtin_amdgcn_ds_read_tr16_b64_v4i16((LAS v4i16_t*)(vp + db * 64 + 24 * VROW));
;                 const bf16x8 va = {a0[0], a0[1], a0[2], a0[3], a1[0], a1[1], a1[2], a1[3]}, vc = {c0[0], c0[1], c0[2], c0[3], c1[0], c1[1], c1[2], c1[3]};
;                 __builtin_amdgcn_s_setprio(1);
;                 if (db == 0) { o0 = MFMA32(va, pb0, o0); o0 = MFMA32(vc, pb1, o0); }
;                 else { o1 = MFMA32(va, pb0, o1); o1 = MFMA32(vc, pb1, o1); }
.LBB0_1046:
	s_nop 8
	v_max3_f32 v16, v0, v1, v2
	v_max3_f32 v17, v3, v4, v5
	v_max3_f32 v18, v6, v7, v8
	v_max3_f32 v19, v9, v10, v11
	v_max3_f32 v16, v16, v17, v18
	v_max3_f32 v17, v12, v13, v14
	v_max3_f32 v16, v16, v19, v17
	v_max_f32_e32 v16, v16, v15
	v_mov_b32_e32 v17, v16
	s_nop 1
	v_permlane32_swap_b32_e32 v16, v17
	v_max_f32_e32 v48, v16, v17
	v_sub_f32_e32 v0, v0, v48
	v_sub_f32_e32 v1, v1, v48
	v_exp_f32_e64 v16, -v48
	v_exp_f32_e32 v0, v0
	v_sub_f32_e32 v2, v2, v48
	v_exp_f32_e32 v1, v1
	v_sub_f32_e32 v3, v3, v48
	v_exp_f32_e32 v2, v2
	v_sub_f32_e32 v4, v4, v48
	v_exp_f32_e32 v3, v3
	v_sub_f32_e32 v5, v5, v48
	v_mul_f32_e32 v32, 0, v16
	v_exp_f32_e32 v4, v4
	v_sub_f32_e32 v6, v6, v48
	v_add_f32_e32 v16, v1, v0
	v_exp_f32_e32 v5, v5
	v_sub_f32_e32 v7, v7, v48
	v_add_f32_e32 v16, v2, v16
	v_exp_f32_e32 v6, v6
	v_sub_f32_e32 v8, v8, v48
	v_add_f32_e32 v16, v3, v16
	v_exp_f32_e32 v7, v7
	v_sub_f32_e32 v9, v9, v48
	v_add_f32_e32 v16, v4, v16
	v_exp_f32_e32 v8, v8
	v_sub_f32_e32 v10, v10, v48
	v_add_f32_e32 v16, v5, v16
	v_exp_f32_e32 v9, v9
	v_sub_f32_e32 v11, v11, v48
	v_add_f32_e32 v16, v6, v16
	v_exp_f32_e32 v10, v10
	v_sub_f32_e32 v12, v12, v48
	v_add_f32_e32 v16, v7, v16
	v_exp_f32_e32 v11, v11
	v_sub_f32_e32 v13, v13, v48
	v_add_f32_e32 v16, v8, v16
	v_exp_f32_e32 v12, v12
	v_sub_f32_e32 v14, v14, v48
	v_add_f32_e32 v16, v9, v16
	v_exp_f32_e32 v13, v13
	v_sub_f32_e32 v15, v15, v48
	v_add_f32_e32 v16, v10, v16
	v_exp_f32_e32 v14, v14
	v_add_f32_e32 v16, v11, v16
	v_exp_f32_e32 v15, v15
	v_add_f32_e32 v16, v12, v16
	v_add_f32_e32 v16, v13, v16
	v_add_f32_e32 v16, v14, v16
	v_add_u32_e32 v24, v119, v115
	v_add_f32_e32 v107, v15, v16
	ds_read_b64_tr_b16 v[16:17], v24 offset:13312
	ds_read_b64_tr_b16 v[18:19], v24 offset:14848
	ds_read_b64_tr_b16 v[20:21], v24 offset:16384
	ds_read_b64_tr_b16 v[22:23], v24 offset:17920
	s_movk_i32 s46, 0xc0
	v_mov_b32_e32 v33, v32
	v_mov_b32_e32 v34, v32
	v_mov_b32_e32 v35, v32
	v_mov_b32_e32 v36, v32
	v_mov_b32_e32 v37, v32
	v_mov_b32_e32 v38, v32
	v_mov_b32_e32 v39, v32
	v_mov_b32_e32 v40, v32
	v_mov_b32_e32 v41, v32
	v_mov_b32_e32 v42, v32
	v_mov_b32_e32 v43, v32
	v_mov_b32_e32 v44, v32
	v_mov_b32_e32 v45, v32
	v_mov_b32_e32 v46, v32
	v_mov_b32_e32 v47, v32
	v_cvt_pk_bf16_f32 v52, v0, v1
	v_cvt_pk_bf16_f32 v56, v8, v9
	v_cvt_pk_bf16_f32 v53, v2, v3
	v_cvt_pk_bf16_f32 v57, v10, v11
	v_cvt_pk_bf16_f32 v54, v4, v5
	v_cvt_pk_bf16_f32 v58, v12, v13
	v_cvt_pk_bf16_f32 v55, v6, v7
	v_cvt_pk_bf16_f32 v59, v14, v15
	s_setprio 1
	s_waitcnt lgkmcnt(2)
	v_mfma_f32_32x32x16_bf16 v[0:15], v[16:19], v[52:55], v[32:47]
	s_waitcnt lgkmcnt(0)
	v_mfma_f32_32x32x16_bf16 v[0:15], v[20:23], v[56:59], v[0:15]
	s_setprio 0
	ds_read_b64_tr_b16 v[60:61], v24 offset:13376
	ds_read_b64_tr_b16 v[62:63], v24 offset:14912
	ds_read_b64_tr_b16 v[120:121], v24 offset:16448
	ds_read_b64_tr_b16 v[122:123], v24 offset:17984
	s_setprio 1
	v_mov_b64_e32 v[16:17], v[32:33]
	v_mov_b64_e32 v[18:19], v[34:35]
	v_mov_b64_e32 v[20:21], v[36:37]
	v_mov_b64_e32 v[22:23], v[38:39]
	v_mov_b64_e32 v[24:25], v[40:41]
	v_mov_b64_e32 v[26:27], v[42:43]
	v_mov_b64_e32 v[28:29], v[44:45]
	v_mov_b64_e32 v[30:31], v[46:47]
	s_waitcnt lgkmcnt(2)
	s_nop 0
	v_mfma_f32_32x32x16_bf16 v[16:31], v[60:63], v[52:55], v[16:31]
	s_waitcnt lgkmcnt(0)
	v_mfma_f32_32x32x16_bf16 v[16:31], v[120:123], v[56:59], v[16:31]
	s_setprio 0
	v_mov_b32_e32 v49, v32
	v_mov_b32_e32 v106, v65
	v_add_f32_e64 v106, v48, v106
	v_add_f32_e64 v107, v49, v107
	v_xor_b32_e32 v32, 0x80000000, v106
	v_mov_b32_e32 v33, v32
	v_mov_b32_e32 v34, v32
	v_mov_b32_e32 v35, v32
	v_mov_b32_e32 v36, v32
	v_mov_b32_e32 v37, v32
	v_mov_b32_e32 v38, v32
	v_mov_b32_e32 v39, v32
	v_mov_b32_e32 v40, v32
	v_mov_b32_e32 v41, v32
	v_mov_b32_e32 v42, v32
	v_mov_b32_e32 v43, v32
	v_mov_b32_e32 v44, v32
	v_mov_b32_e32 v45, v32
	v_mov_b32_e32 v46, v32
	v_mov_b32_e32 v47, v32
	s_branch .LBB0_1048

; __device__ __forceinline__ unsigned cvt_pk_bf16(float lo, float hi) { const f32x2c_ v = {lo, hi}; const bf16x2c_ b = __builtin_convertvector(v, bf16x2c_); return __builtin_bit_cast(unsigned, b); }
; __device__ __forceinline__ void attn_unit(int bh, int qb, const bf16_t* QKV, const bf16_t* KF, const float* cstab, const float* qg, bf16_t* MIX, LAS unsigned char* lds) {
;     ...
;             float mx = fmaxf(fmaxf(p[0], p[1]), fmaxf(p[2], p[3]));
; #pragma unroll
;             for (int r = 4; r < 16; r += 4) mx = fmaxf(mx, fmaxf(fmaxf(p[r], p[r + 1]), fmaxf(p[r + 2], p[r + 3])));
;             mx = pg8::max32(mx);
;             if (key0 == 0 || __any(mx > 4.0f)) {
;                 const float dl = (key0 == 0) ? mx : fmaxf(mx, 0.f), f = __builtin_amdgcn_exp2f(-dl);
;                 mrun += dl; lrun *= f;
; #pragma unroll
;                 for (int r = 0; r < 16; ++r) { o0[r] *= f; o1[r] *= f; p[r] -= dl; negm[r] = -mrun; }
;             }
;             float ps = 0.f;
; #pragma unroll
;             for (int r = 0; r < 16; ++r) { p[r] = __builtin_amdgcn_exp2f(p[r]); ps += p[r]; }
;             lrun += ps;
;             u32x4 w0, w1;
; #pragma unroll
;             for (int k = 0; k < 4; ++k) { w0[k] = cvt_pk_bf16(p[2 * k], p[2 * k + 1]); w1[k] = cvt_pk_bf16(p[8 + 2 * k], p[8 + 2 * k + 1]); }
;             const bf16x8 pb0 = __builtin_bit_cast(bf16x8, w0), pb1 = __builtin_bit_cast(bf16x8, w1);
;             const LAS unsigned char* vp = buf + vtb + (32 * kb) * VROW;
; #pragma unroll
;             for (int db = 0; db < 2; ++db) {
;                 const v4i16_t a0 = __builtin_amdgcn_ds_read_tr16_b64_v4i16((LAS v4i16_t*)(vp + db * 64));
;                 const v4i16_t a1 = __builtin_amdgcn_ds_read_tr16_b64_v4i16((LAS v4i16_t*)(vp + db * 64 + 8 * VROW));
;                 const v4i16_t c0 = __builtin_amdgcn_ds_read_tr16_b64_v4i16((LAS v4i16_t*)(vp + db * 64 + 16 * VROW));
;                 const v4i16_t c1 = __builtin_amdgcn_ds_read_tr16_b64_v4i16((LAS v4i16_t*)(vp + db * 64 + 24 * VROW));
;                 const bf16x8 va = {a0[0], a0[1], a0[2], a0[3], a1[0], a1[1], a1[2], a1[3]}, vc = {c0[0], c0[1], c0[2], c0[3], c1[0], c1[1], c1[2], c1[3]};
;                 __builtin_amdgcn_s_setprio(1);
;                 if (db == 0) { o0 = MFMA32(va, pb0, o0); o0 = MFMA32(vc, pb1, o0); }
;                 else { o1 = MFMA32(va, pb0, o1); o1 = MFMA32(vc, pb1, o1); }
.LBB0_1051:
	s_nop 8
	v_max3_f32 v120, v48, v49, v50
	v_max3_f32 v121, v51, v52, v53
	v_max3_f32 v122, v54, v55, v56
	v_max3_f32 v123, v57, v58, v59
	v_max3_f32 v120, v120, v121, v122
	v_max3_f32 v121, v60, v61, v62
	v_max3_f32 v120, v120, v123, v121
	v_max_f32_e32 v120, v120, v63
	v_mov_b32_e32 v121, v120
	s_nop 1
	v_permlane32_swap_b32_e32 v120, v121
	v_max_f32_e32 v120, v120, v121
	v_cmp_lt_f32_e32 vcc, 4.0, v120
	s_cbranch_vccz .LBB0_1053
	v_max_f32_e32 v32, v120, v120
	v_max_f32_e32 v34, 0, v32
	v_exp_f32_e64 v120, -v34
	v_add_f32_e32 v106, v106, v34
	v_xor_b32_e32 v32, 0x80000000, v106
	v_pk_add_f32 v[48:49], v[48:49], v[34:35] op_sel_hi:[1,0] neg_lo:[0,1] neg_hi:[0,1]
	v_pk_add_f32 v[50:51], v[50:51], v[34:35] op_sel_hi:[1,0] neg_lo:[0,1] neg_hi:[0,1]
	v_pk_add_f32 v[52:53], v[52:53], v[34:35] op_sel_hi:[1,0] neg_lo:[0,1] neg_hi:[0,1]
	v_pk_add_f32 v[54:55], v[54:55], v[34:35] op_sel_hi:[1,0] neg_lo:[0,1] neg_hi:[0,1]
	v_pk_add_f32 v[56:57], v[56:57], v[34:35] op_sel_hi:[1,0] neg_lo:[0,1] neg_hi:[0,1]
	v_pk_add_f32 v[58:59], v[58:59], v[34:35] op_sel_hi:[1,0] neg_lo:[0,1] neg_hi:[0,1]
	v_pk_add_f32 v[60:61], v[60:61], v[34:35] op_sel_hi:[1,0] neg_lo:[0,1] neg_hi:[0,1]
	v_pk_mul_f32 v[14:15], v[14:15], v[120:121] op_sel_hi:[1,0]
	v_pk_mul_f32 v[12:13], v[12:13], v[120:121] op_sel_hi:[1,0]
	v_pk_mul_f32 v[10:11], v[10:11], v[120:121] op_sel_hi:[1,0]
	v_pk_mul_f32 v[8:9], v[8:9], v[120:121] op_sel_hi:[1,0]
	v_pk_mul_f32 v[6:7], v[6:7], v[120:121] op_sel_hi:[1,0]
	v_pk_mul_f32 v[4:5], v[4:5], v[120:121] op_sel_hi:[1,0]
	v_pk_mul_f32 v[2:3], v[2:3], v[120:121] op_sel_hi:[1,0]
	v_pk_mul_f32 v[0:1], v[0:1], v[120:121] op_sel_hi:[1,0]
	v_pk_mul_f32 v[30:31], v[30:31], v[120:121] op_sel_hi:[1,0]
	v_pk_mul_f32 v[28:29], v[28:29], v[120:121] op_sel_hi:[1,0]
	v_pk_mul_f32 v[26:27], v[26:27], v[120:121] op_sel_hi:[1,0]
	v_pk_mul_f32 v[24:25], v[24:25], v[120:121] op_sel_hi:[1,0]
	v_pk_mul_f32 v[22:23], v[22:23], v[120:121] op_sel_hi:[1,0]
	v_pk_mul_f32 v[20:21], v[20:21], v[120:121] op_sel_hi:[1,0]
	v_pk_mul_f32 v[18:19], v[18:19], v[120:121] op_sel_hi:[1,0]
	v_pk_mul_f32 v[16:17], v[16:17], v[120:121] op_sel_hi:[1,0]
	v_pk_add_f32 v[62:63], v[62:63], v[34:35] op_sel_hi:[1,0] neg_lo:[0,1] neg_hi:[0,1]
	v_mov_b32_e32 v33, v32
	v_mov_b32_e32 v34, v32
	v_mov_b32_e32 v35, v32
	v_mov_b32_e32 v36, v32
	v_mov_b32_e32 v37, v32
	v_mov_b32_e32 v38, v32
	v_mov_b32_e32 v39, v32
	v_mov_b32_e32 v40, v32
	v_mov_b32_e32 v41, v32
	v_mov_b32_e32 v42, v32
	v_mov_b32_e32 v43, v32
	v_mov_b32_e32 v44, v32
	v_mov_b32_e32 v45, v32
	v_mov_b32_e32 v46, v32
	v_mov_b32_e32 v47, v32
	v_mul_f32_e32 v107, v107, v120
.LBB0_1053:
	v_exp_f32_e32 v48, v48
	v_exp_f32_e32 v49, v49
	v_exp_f32_e32 v50, v50
	v_exp_f32_e32 v51, v51
	v_exp_f32_e32 v121, v52
	v_add_f32_e32 v120, v49, v48
	v_add_f32_e32 v120, v50, v120
	v_add_f32_e32 v120, v51, v120
	v_add_f32_e32 v52, v121, v120
	v_exp_f32_e32 v120, v53
	v_exp_f32_e32 v122, v54
	v_exp_f32_e32 v55, v55
	v_exp_f32_e32 v53, v56
	v_add_f32_e32 v52, v120, v52
	v_exp_f32_e32 v54, v57
	v_add_f32_e32 v52, v122, v52
	v_exp_f32_e32 v56, v58
	v_add_f32_e32 v52, v55, v52
	v_exp_f32_e32 v57, v59
	v_add_f32_e32 v52, v53, v52
	v_exp_f32_e32 v58, v60
	v_add_f32_e32 v52, v54, v52
	v_exp_f32_e32 v59, v61
	v_add_f32_e32 v52, v56, v52
	v_exp_f32_e32 v60, v62
	v_add_f32_e32 v52, v57, v52
	v_exp_f32_e32 v61, v63
	v_add_f32_e32 v52, v58, v52
	v_add_f32_e32 v52, v59, v52
	v_add_f32_e32 v52, v60, v52
	v_add_u32_e32 v119, v119, v115
	v_add_f32_e32 v123, v61, v52
	v_cvt_pk_bf16_f32 v48, v48, v49
	v_cvt_pk_bf16_f32 v52, v53, v54
	v_cvt_pk_bf16_f32 v49, v50, v51
	v_cvt_pk_bf16_f32 v53, v56, v57
	v_cvt_pk_bf16_f32 v54, v58, v59
	v_cvt_pk_bf16_f32 v51, v122, v55
	v_cvt_pk_bf16_f32 v55, v60, v61
	ds_read_b64_tr_b16 v[56:57], v119 offset:19456
	ds_read_b64_tr_b16 v[58:59], v119 offset:20992
	ds_read_b64_tr_b16 v[60:61], v119 offset:22528
	ds_read_b64_tr_b16 v[62:63], v119 offset:24064
	v_cvt_pk_bf16_f32 v50, v121, v120
	s_setprio 1
	s_waitcnt lgkmcnt(2)
	v_mfma_f32_32x32x16_bf16 v[0:15], v[56:59], v[48:51], v[0:15]
	s_waitcnt lgkmcnt(0)
	v_mfma_f32_32x32x16_bf16 v[0:15], v[60:63], v[52:55], v[0:15]
	s_setprio 0
	ds_read_b64_tr_b16 v[56:57], v119 offset:19520
	ds_read_b64_tr_b16 v[58:59], v119 offset:21056
	ds_read_b64_tr_b16 v[60:61], v119 offset:22592
	ds_read_b64_tr_b16 v[62:63], v119 offset:24128
	s_setprio 1
	s_waitcnt lgkmcnt(2)
	v_mfma_f32_32x32x16_bf16 v[16:31], v[56:59], v[48:51], v[16:31]
	s_waitcnt lgkmcnt(0)
	v_mfma_f32_32x32x16_bf16 v[16:31], v[60:63], v[52:55], v[16:31]
	s_setprio 0
	v_add_f32_e32 v107, v107, v123

; __device__ __forceinline__ unsigned cvt_pk_bf16(float lo, float hi) { const f32x2c_ v = {lo, hi}; const bf16x2c_ b = __builtin_convertvector(v, bf16x2c_); return __builtin_bit_cast(unsigned, b); }
; __device__ __forceinline__ void attn_unit(int bh, int qb, const bf16_t* QKV, const bf16_t* KF, const float* cstab, const float* qg, bf16_t* MIX, LAS unsigned char* lds) {
;     ...
;             float mx = fmaxf(fmaxf(p[0], p[1]), fmaxf(p[2], p[3]));
; #pragma unroll
;             for (int r = 4; r < 16; r += 4) mx = fmaxf(mx, fmaxf(fmaxf(p[r], p[r + 1]), fmaxf(p[r + 2], p[r + 3])));
;             mx = pg8::max32(mx);
;             if (key0 == 0 || __any(mx > 4.0f)) {
;                 const float dl = (key0 == 0) ? mx : fmaxf(mx, 0.f), f = __builtin_amdgcn_exp2f(-dl);
;                 mrun += dl; lrun *= f;
; #pragma unroll
;                 for (int r = 0; r < 16; ++r) { o0[r] *= f; o1[r] *= f; p[r] -= dl; negm[r] = -mrun; }
;             }
;             float ps = 0.f;
; #pragma unroll
;             for (int r = 0; r < 16; ++r) { p[r] = __builtin_amdgcn_exp2f(p[r]); ps += p[r]; }
;             lrun += ps;
;             u32x4 w0, w1;
; #pragma unroll
;             for (int k = 0; k < 4; ++k) { w0[k] = cvt_pk_bf16(p[2 * k], p[2 * k + 1]); w1[k] = cvt_pk_bf16(p[8 + 2 * k], p[8 + 2 * k + 1]); }
;             const bf16x8 pb0 = __builtin_bit_cast(bf16x8, w0), pb1 = __builtin_bit_cast(bf16x8, w1);
;             const LAS unsigned char* vp = buf + vtb + (32 * kb) * VROW;
; #pragma unroll
;             for (int db = 0; db < 2; ++db) {
;                 const v4i16_t a0 = __builtin_amdgcn_ds_read_tr16_b64_v4i16((LAS v4i16_t*)(vp + db * 64));
;                 const v4i16_t a1 = __builtin_amdgcn_ds_read_tr16_b64_v4i16((LAS v4i16_t*)(vp + db * 64 + 8 * VROW));
;                 const v4i16_t c0 = __builtin_amdgcn_ds_read_tr16_b64_v4i16((LAS v4i16_t*)(vp + db * 64 + 16 * VROW));
;                 const v4i16_t c1 = __builtin_amdgcn_ds_read_tr16_b64_v4i16((LAS v4i16_t*)(vp + db * 64 + 24 * VROW));
;                 const bf16x8 va = {a0[0], a0[1], a0[2], a0[3], a1[0], a1[1], a1[2], a1[3]}, vc = {c0[0], c0[1], c0[2], c0[3], c1[0], c1[1], c1[2], c1[3]};
;                 __builtin_amdgcn_s_setprio(1);
;                 if (db == 0) { o0 = MFMA32(va, pb0, o0); o0 = MFMA32(vc, pb1, o0); }
;                 else { o1 = MFMA32(va, pb0, o1); o1 = MFMA32(vc, pb1, o1); }
.LBB0_1064:
	s_nop 7
	v_max3_f32 v121, v48, v49, v50
	v_max3_f32 v122, v51, v52, v53
	v_max3_f32 v123, v54, v55, v56
	v_max3_f32 v124, v57, v58, v59
	v_max3_f32 v121, v121, v122, v123
	v_max3_f32 v122, v60, v61, v62
	v_max3_f32 v121, v121, v124, v122
	v_max_f32_e32 v121, v121, v63
	v_mov_b32_e32 v122, v121
	s_nop 1
	v_permlane32_swap_b32_e32 v121, v122
	v_max_f32_e32 v121, v121, v122
	v_cmp_lt_f32_e32 vcc, 4.0, v121
	s_cbranch_vccz .LBB0_1066
	v_max_f32_e32 v32, v121, v121
	v_max_f32_e32 v34, 0, v32
	v_exp_f32_e64 v122, -v34
	v_add_f32_e32 v106, v106, v34
	v_xor_b32_e32 v32, 0x80000000, v106
	v_pk_add_f32 v[48:49], v[48:49], v[34:35] op_sel_hi:[1,0] neg_lo:[0,1] neg_hi:[0,1]
	v_pk_add_f32 v[50:51], v[50:51], v[34:35] op_sel_hi:[1,0] neg_lo:[0,1] neg_hi:[0,1]
	v_pk_add_f32 v[52:53], v[52:53], v[34:35] op_sel_hi:[1,0] neg_lo:[0,1] neg_hi:[0,1]
	v_pk_add_f32 v[54:55], v[54:55], v[34:35] op_sel_hi:[1,0] neg_lo:[0,1] neg_hi:[0,1]
	v_pk_add_f32 v[56:57], v[56:57], v[34:35] op_sel_hi:[1,0] neg_lo:[0,1] neg_hi:[0,1]
	v_pk_add_f32 v[58:59], v[58:59], v[34:35] op_sel_hi:[1,0] neg_lo:[0,1] neg_hi:[0,1]
	v_pk_add_f32 v[60:61], v[60:61], v[34:35] op_sel_hi:[1,0] neg_lo:[0,1] neg_hi:[0,1]
	v_pk_mul_f32 v[14:15], v[14:15], v[122:123] op_sel_hi:[1,0]
	v_pk_mul_f32 v[12:13], v[12:13], v[122:123] op_sel_hi:[1,0]
	v_pk_mul_f32 v[10:11], v[10:11], v[122:123] op_sel_hi:[1,0]
	v_pk_mul_f32 v[8:9], v[8:9], v[122:123] op_sel_hi:[1,0]
	v_pk_mul_f32 v[6:7], v[6:7], v[122:123] op_sel_hi:[1,0]
	v_pk_mul_f32 v[4:5], v[4:5], v[122:123] op_sel_hi:[1,0]
	v_pk_mul_f32 v[2:3], v[2:3], v[122:123] op_sel_hi:[1,0]
	v_pk_mul_f32 v[0:1], v[0:1], v[122:123] op_sel_hi:[1,0]
	v_pk_mul_f32 v[30:31], v[30:31], v[122:123] op_sel_hi:[1,0]
	v_pk_mul_f32 v[28:29], v[28:29], v[122:123] op_sel_hi:[1,0]
	v_pk_mul_f32 v[26:27], v[26:27], v[122:123] op_sel_hi:[1,0]
	v_pk_mul_f32 v[24:25], v[24:25], v[122:123] op_sel_hi:[1,0]
	v_pk_mul_f32 v[22:23], v[22:23], v[122:123] op_sel_hi:[1,0]
	v_pk_mul_f32 v[20:21], v[20:21], v[122:123] op_sel_hi:[1,0]
	v_pk_mul_f32 v[18:19], v[18:19], v[122:123] op_sel_hi:[1,0]
	v_pk_mul_f32 v[16:17], v[16:17], v[122:123] op_sel_hi:[1,0]
	v_pk_add_f32 v[62:63], v[62:63], v[34:35] op_sel_hi:[1,0] neg_lo:[0,1] neg_hi:[0,1]
	v_mov_b32_e32 v33, v32
	v_mov_b32_e32 v34, v32
	v_mov_b32_e32 v35, v32
	v_mov_b32_e32 v36, v32
	v_mov_b32_e32 v37, v32
	v_mov_b32_e32 v38, v32
	v_mov_b32_e32 v39, v32
	v_mov_b32_e32 v40, v32
	v_mov_b32_e32 v41, v32
	v_mov_b32_e32 v42, v32
	v_mov_b32_e32 v43, v32
	v_mov_b32_e32 v44, v32
	v_mov_b32_e32 v45, v32
	v_mov_b32_e32 v46, v32
	v_mov_b32_e32 v47, v32
	v_mul_f32_e32 v107, v107, v122
.LBB0_1066:
	v_exp_f32_e32 v48, v48
	v_exp_f32_e32 v49, v49
	v_exp_f32_e32 v50, v50
	v_exp_f32_e32 v51, v51
	v_exp_f32_e32 v122, v52
	v_add_f32_e32 v121, v49, v48
	v_add_f32_e32 v121, v50, v121
	v_add_f32_e32 v121, v51, v121
	v_add_f32_e32 v52, v122, v121
	v_exp_f32_e32 v121, v53
	v_exp_f32_e32 v123, v54
	v_exp_f32_e32 v55, v55
	v_exp_f32_e32 v53, v56
	v_add_f32_e32 v52, v121, v52
	v_exp_f32_e32 v54, v57
	v_add_f32_e32 v52, v123, v52
	v_exp_f32_e32 v56, v58
	v_add_f32_e32 v52, v55, v52
	v_exp_f32_e32 v57, v59
	v_add_f32_e32 v52, v53, v52
	v_exp_f32_e32 v58, v60
	v_add_f32_e32 v52, v54, v52
	v_exp_f32_e32 v59, v61
	v_add_f32_e32 v52, v56, v52
	v_exp_f32_e32 v60, v62
	v_add_f32_e32 v52, v57, v52
	v_exp_f32_e32 v61, v63
	v_add_f32_e32 v52, v58, v52
	v_add_f32_e32 v52, v59, v52
	v_add_f32_e32 v52, v60, v52
	v_cvt_pk_bf16_f32 v48, v48, v49
	v_cvt_pk_bf16_f32 v49, v50, v51
	v_cvt_pk_bf16_f32 v50, v122, v121
	v_add_u32_e32 v121, v119, v115
	v_add_f32_e32 v124, v61, v52
	v_cvt_pk_bf16_f32 v52, v53, v54
	v_cvt_pk_bf16_f32 v53, v56, v57
	v_cvt_pk_bf16_f32 v54, v58, v59
	v_cvt_pk_bf16_f32 v51, v123, v55
	v_cvt_pk_bf16_f32 v55, v60, v61
	ds_read_b64_tr_b16 v[56:57], v121 offset:13312
	ds_read_b64_tr_b16 v[58:59], v121 offset:14848
	ds_read_b64_tr_b16 v[60:61], v121 offset:16384
	ds_read_b64_tr_b16 v[62:63], v121 offset:17920
	s_setprio 1
	s_waitcnt lgkmcnt(2)
	v_mfma_f32_32x32x16_bf16 v[0:15], v[56:59], v[48:51], v[0:15]
	s_waitcnt lgkmcnt(0)
	v_mfma_f32_32x32x16_bf16 v[0:15], v[60:63], v[52:55], v[0:15]
	s_setprio 0
	ds_read_b64_tr_b16 v[56:57], v121 offset:13376
	ds_read_b64_tr_b16 v[58:59], v121 offset:14912
	ds_read_b64_tr_b16 v[60:61], v121 offset:16448
	ds_read_b64_tr_b16 v[62:63], v121 offset:17984
	s_setprio 1
	s_waitcnt lgkmcnt(2)
	v_mfma_f32_32x32x16_bf16 v[16:31], v[56:59], v[48:51], v[16:31]
	s_waitcnt lgkmcnt(0)
	v_mfma_f32_32x32x16_bf16 v[16:31], v[60:63], v[52:55], v[16:31]
	s_setprio 0
	v_add_f32_e32 v107, v107, v124
	s_add_i32 s44, s43, 0x60
	s_cmp_gt_i32 s44, s2
	s_cbranch_scc0 .LBB0_1069

; __device__ __forceinline__ unsigned cvt_pk_bf16(float lo, float hi) { const f32x2c_ v = {lo, hi}; const bf16x2c_ b = __builtin_convertvector(v, bf16x2c_); return __builtin_bit_cast(unsigned, b); }
; __device__ __forceinline__ void attn_unit(int bh, int qb, const bf16_t* QKV, const bf16_t* KF, const float* cstab, const float* qg, bf16_t* MIX, LAS unsigned char* lds) {
;     ...
;             float mx = fmaxf(fmaxf(p[0], p[1]), fmaxf(p[2], p[3]));
; #pragma unroll
;             for (int r = 4; r < 16; r += 4) mx = fmaxf(mx, fmaxf(fmaxf(p[r], p[r + 1]), fmaxf(p[r + 2], p[r + 3])));
;             mx = pg8::max32(mx);
;             if (key0 == 0 || __any(mx > 4.0f)) {
;                 const float dl = (key0 == 0) ? mx : fmaxf(mx, 0.f), f = __builtin_amdgcn_exp2f(-dl);
;                 mrun += dl; lrun *= f;
; #pragma unroll
;                 for (int r = 0; r < 16; ++r) { o0[r] *= f; o1[r] *= f; p[r] -= dl; negm[r] = -mrun; }
;             }
;             float ps = 0.f;
; #pragma unroll
;             for (int r = 0; r < 16; ++r) { p[r] = __builtin_amdgcn_exp2f(p[r]); ps += p[r]; }
;             lrun += ps;
;             u32x4 w0, w1;
; #pragma unroll
;             for (int k = 0; k < 4; ++k) { w0[k] = cvt_pk_bf16(p[2 * k], p[2 * k + 1]); w1[k] = cvt_pk_bf16(p[8 + 2 * k], p[8 + 2 * k + 1]); }
;             const bf16x8 pb0 = __builtin_bit_cast(bf16x8, w0), pb1 = __builtin_bit_cast(bf16x8, w1);
;             const LAS unsigned char* vp = buf + vtb + (32 * kb) * VROW;
; #pragma unroll
;             for (int db = 0; db < 2; ++db) {
;                 const v4i16_t a0 = __builtin_amdgcn_ds_read_tr16_b64_v4i16((LAS v4i16_t*)(vp + db * 64));
;                 const v4i16_t a1 = __builtin_amdgcn_ds_read_tr16_b64_v4i16((LAS v4i16_t*)(vp + db * 64 + 8 * VROW));
;                 const v4i16_t c0 = __builtin_amdgcn_ds_read_tr16_b64_v4i16((LAS v4i16_t*)(vp + db * 64 + 16 * VROW));
;                 const v4i16_t c1 = __builtin_amdgcn_ds_read_tr16_b64_v4i16((LAS v4i16_t*)(vp + db * 64 + 24 * VROW));
;                 const bf16x8 va = {a0[0], a0[1], a0[2], a0[3], a1[0], a1[1], a1[2], a1[3]}, vc = {c0[0], c0[1], c0[2], c0[3], c1[0], c1[1], c1[2], c1[3]};
;                 __builtin_amdgcn_s_setprio(1);
;                 if (db == 0) { o0 = MFMA32(va, pb0, o0); o0 = MFMA32(vc, pb1, o0); }
;                 else { o1 = MFMA32(va, pb0, o1); o1 = MFMA32(vc, pb1, o1); }
.LBB0_1071:
	s_nop 7
	v_max3_f32 v120, v48, v49, v50
	v_max3_f32 v121, v51, v52, v53
	v_max3_f32 v122, v54, v55, v56
	v_max3_f32 v123, v57, v58, v59
	v_max3_f32 v120, v120, v121, v122
	v_max3_f32 v121, v60, v61, v62
	v_max3_f32 v120, v120, v123, v121
	v_max_f32_e32 v120, v120, v63
	v_mov_b32_e32 v121, v120
	s_nop 1
	v_permlane32_swap_b32_e32 v120, v121
	v_max_f32_e32 v120, v120, v121
	v_cmp_lt_f32_e32 vcc, 4.0, v120
	s_cbranch_vccz .LBB0_1073
	v_max_f32_e32 v32, v120, v120
	v_max_f32_e32 v34, 0, v32
	v_exp_f32_e64 v120, -v34
	v_add_f32_e32 v106, v106, v34
	v_xor_b32_e32 v32, 0x80000000, v106
	v_pk_add_f32 v[48:49], v[48:49], v[34:35] op_sel_hi:[1,0] neg_lo:[0,1] neg_hi:[0,1]
	v_pk_add_f32 v[50:51], v[50:51], v[34:35] op_sel_hi:[1,0] neg_lo:[0,1] neg_hi:[0,1]
	v_pk_add_f32 v[52:53], v[52:53], v[34:35] op_sel_hi:[1,0] neg_lo:[0,1] neg_hi:[0,1]
	v_pk_add_f32 v[54:55], v[54:55], v[34:35] op_sel_hi:[1,0] neg_lo:[0,1] neg_hi:[0,1]
	v_pk_add_f32 v[56:57], v[56:57], v[34:35] op_sel_hi:[1,0] neg_lo:[0,1] neg_hi:[0,1]
	v_pk_add_f32 v[58:59], v[58:59], v[34:35] op_sel_hi:[1,0] neg_lo:[0,1] neg_hi:[0,1]
	v_pk_add_f32 v[60:61], v[60:61], v[34:35] op_sel_hi:[1,0] neg_lo:[0,1] neg_hi:[0,1]
	v_pk_mul_f32 v[14:15], v[14:15], v[120:121] op_sel_hi:[1,0]
	v_pk_mul_f32 v[12:13], v[12:13], v[120:121] op_sel_hi:[1,0]
	v_pk_mul_f32 v[10:11], v[10:11], v[120:121] op_sel_hi:[1,0]
	v_pk_mul_f32 v[8:9], v[8:9], v[120:121] op_sel_hi:[1,0]
	v_pk_mul_f32 v[6:7], v[6:7], v[120:121] op_sel_hi:[1,0]
	v_pk_mul_f32 v[4:5], v[4:5], v[120:121] op_sel_hi:[1,0]
	v_pk_mul_f32 v[2:3], v[2:3], v[120:121] op_sel_hi:[1,0]
	v_pk_mul_f32 v[0:1], v[0:1], v[120:121] op_sel_hi:[1,0]
	v_pk_mul_f32 v[30:31], v[30:31], v[120:121] op_sel_hi:[1,0]
	v_pk_mul_f32 v[28:29], v[28:29], v[120:121] op_sel_hi:[1,0]
	v_pk_mul_f32 v[26:27], v[26:27], v[120:121] op_sel_hi:[1,0]
	v_pk_mul_f32 v[24:25], v[24:25], v[120:121] op_sel_hi:[1,0]
	v_pk_mul_f32 v[22:23], v[22:23], v[120:121] op_sel_hi:[1,0]
	v_pk_mul_f32 v[20:21], v[20:21], v[120:121] op_sel_hi:[1,0]
	v_pk_mul_f32 v[18:19], v[18:19], v[120:121] op_sel_hi:[1,0]
	v_pk_mul_f32 v[16:17], v[16:17], v[120:121] op_sel_hi:[1,0]
	v_pk_add_f32 v[62:63], v[62:63], v[34:35] op_sel_hi:[1,0] neg_lo:[0,1] neg_hi:[0,1]
	v_mov_b32_e32 v33, v32
	v_mov_b32_e32 v34, v32
	v_mov_b32_e32 v35, v32
	v_mov_b32_e32 v36, v32
	v_mov_b32_e32 v37, v32
	v_mov_b32_e32 v38, v32
	v_mov_b32_e32 v39, v32
	v_mov_b32_e32 v40, v32
	v_mov_b32_e32 v41, v32
	v_mov_b32_e32 v42, v32
	v_mov_b32_e32 v43, v32
	v_mov_b32_e32 v44, v32
	v_mov_b32_e32 v45, v32
	v_mov_b32_e32 v46, v32
	v_mov_b32_e32 v47, v32
	v_mul_f32_e32 v107, v107, v120
.LBB0_1073:
	v_exp_f32_e32 v48, v48
	v_exp_f32_e32 v49, v49
	v_exp_f32_e32 v50, v50
	v_exp_f32_e32 v51, v51
	v_exp_f32_e32 v121, v52
	v_add_f32_e32 v120, v49, v48
	v_add_f32_e32 v120, v50, v120
	v_add_f32_e32 v120, v51, v120
	v_add_f32_e32 v52, v121, v120
	v_exp_f32_e32 v120, v53
	v_exp_f32_e32 v122, v54
	v_exp_f32_e32 v55, v55
	v_exp_f32_e32 v53, v56
	v_add_f32_e32 v52, v120, v52
	v_exp_f32_e32 v54, v57
	v_add_f32_e32 v52, v122, v52
	v_exp_f32_e32 v56, v58
	v_add_f32_e32 v52, v55, v52
	v_exp_f32_e32 v57, v59
	v_add_f32_e32 v52, v53, v52
	v_exp_f32_e32 v58, v60
	v_add_f32_e32 v52, v54, v52
	v_exp_f32_e32 v59, v61
	v_add_f32_e32 v52, v56, v52
	v_exp_f32_e32 v60, v62
	v_add_f32_e32 v52, v57, v52
	v_exp_f32_e32 v61, v63
	v_add_f32_e32 v52, v58, v52
	v_add_f32_e32 v52, v59, v52
	v_add_f32_e32 v52, v60, v52
	v_add_u32_e32 v119, v119, v115
	v_add_f32_e32 v123, v61, v52
	v_cvt_pk_bf16_f32 v48, v48, v49
	v_cvt_pk_bf16_f32 v52, v53, v54
	v_cvt_pk_bf16_f32 v49, v50, v51
	v_cvt_pk_bf16_f32 v53, v56, v57
	v_cvt_pk_bf16_f32 v54, v58, v59
	v_cvt_pk_bf16_f32 v51, v122, v55
	v_cvt_pk_bf16_f32 v55, v60, v61
	ds_read_b64_tr_b16 v[56:57], v119 offset:19456
	ds_read_b64_tr_b16 v[58:59], v119 offset:20992
	ds_read_b64_tr_b16 v[60:61], v119 offset:22528
	ds_read_b64_tr_b16 v[62:63], v119 offset:24064
	v_cvt_pk_bf16_f32 v50, v121, v120
	s_setprio 1
	s_waitcnt lgkmcnt(2)
	v_mfma_f32_32x32x16_bf16 v[0:15], v[56:59], v[48:51], v[0:15]
	s_waitcnt lgkmcnt(0)
	v_mfma_f32_32x32x16_bf16 v[0:15], v[60:63], v[52:55], v[0:15]
	s_setprio 0
	ds_read_b64_tr_b16 v[56:57], v119 offset:19520
	ds_read_b64_tr_b16 v[58:59], v119 offset:21056
	ds_read_b64_tr_b16 v[60:61], v119 offset:22592
	ds_read_b64_tr_b16 v[62:63], v119 offset:24128
	s_setprio 1
	s_waitcnt lgkmcnt(2)
	v_mfma_f32_32x32x16_bf16 v[16:31], v[56:59], v[48:51], v[16:31]
	s_waitcnt lgkmcnt(0)
	v_mfma_f32_32x32x16_bf16 v[16:31], v[60:63], v[52:55], v[16:31]
	s_setprio 0
	v_add_f32_e32 v107, v107, v123
	s_andn2_b64 vcc, exec, s[4:5]
	s_cbranch_vccnz .LBB0_1077

; __device__ __forceinline__ unsigned cvt_pk_bf16(float lo, float hi) { const f32x2c_ v = {lo, hi}; const bf16x2c_ b = __builtin_convertvector(v, bf16x2c_); return __builtin_bit_cast(unsigned, b); }
; __device__ __forceinline__ void attn_unit(int bh, int qb, const bf16_t* QKV, const bf16_t* KF, const float* cstab, const float* qg, bf16_t* MIX, LAS unsigned char* lds) {
;     ...
;             float mx = fmaxf(fmaxf(p[0], p[1]), fmaxf(p[2], p[3]));
; #pragma unroll
;             for (int r = 4; r < 16; r += 4) mx = fmaxf(mx, fmaxf(fmaxf(p[r], p[r + 1]), fmaxf(p[r + 2], p[r + 3])));
;             mx = pg8::max32(mx);
;             if (key0 == 0 || __any(mx > 4.0f)) {
;                 const float dl = (key0 == 0) ? mx : fmaxf(mx, 0.f), f = __builtin_amdgcn_exp2f(-dl);
;                 mrun += dl; lrun *= f;
; #pragma unroll
;                 for (int r = 0; r < 16; ++r) { o0[r] *= f; o1[r] *= f; p[r] -= dl; negm[r] = -mrun; }
;             }
;             float ps = 0.f;
; #pragma unroll
;             for (int r = 0; r < 16; ++r) { p[r] = __builtin_amdgcn_exp2f(p[r]); ps += p[r]; }
;             lrun += ps;
;             u32x4 w0, w1;
; #pragma unroll
;             for (int k = 0; k < 4; ++k) { w0[k] = cvt_pk_bf16(p[2 * k], p[2 * k + 1]); w1[k] = cvt_pk_bf16(p[8 + 2 * k], p[8 + 2 * k + 1]); }
;             const bf16x8 pb0 = __builtin_bit_cast(bf16x8, w0), pb1 = __builtin_bit_cast(bf16x8, w1);
;             const LAS unsigned char* vp = buf + vtb + (32 * kb) * VROW;
; #pragma unroll
;             for (int db = 0; db < 2; ++db) {
;                 const v4i16_t a0 = __builtin_amdgcn_ds_read_tr16_b64_v4i16((LAS v4i16_t*)(vp + db * 64));
;                 const v4i16_t a1 = __builtin_amdgcn_ds_read_tr16_b64_v4i16((LAS v4i16_t*)(vp + db * 64 + 8 * VROW));
;                 const v4i16_t c0 = __builtin_amdgcn_ds_read_tr16_b64_v4i16((LAS v4i16_t*)(vp + db * 64 + 16 * VROW));
;                 const v4i16_t c1 = __builtin_amdgcn_ds_read_tr16_b64_v4i16((LAS v4i16_t*)(vp + db * 64 + 24 * VROW));
;                 const bf16x8 va = {a0[0], a0[1], a0[2], a0[3], a1[0], a1[1], a1[2], a1[3]}, vc = {c0[0], c0[1], c0[2], c0[3], c1[0], c1[1], c1[2], c1[3]};
;                 __builtin_amdgcn_s_setprio(1);
;                 if (db == 0) { o0 = MFMA32(va, pb0, o0); o0 = MFMA32(vc, pb1, o0); }
;                 else { o1 = MFMA32(va, pb0, o1); o1 = MFMA32(vc, pb1, o1); }
.LBB0_1087:
	s_nop 8
	v_max3_f32 v16, v0, v1, v2
	v_max3_f32 v17, v3, v4, v5
	v_max3_f32 v18, v6, v7, v8
	v_max3_f32 v19, v9, v10, v11
	v_max3_f32 v16, v16, v17, v18
	v_max3_f32 v17, v12, v13, v14
	v_max3_f32 v16, v16, v19, v17
	v_max_f32_e32 v16, v16, v15
	v_mov_b32_e32 v17, v16
	s_nop 1
	v_permlane32_swap_b32_e32 v16, v17
	v_max_f32_e32 v48, v16, v17
	v_sub_f32_e32 v0, v0, v48
	v_sub_f32_e32 v1, v1, v48
	v_exp_f32_e64 v16, -v48
	v_exp_f32_e32 v0, v0
	v_sub_f32_e32 v2, v2, v48
	v_exp_f32_e32 v1, v1
	v_sub_f32_e32 v3, v3, v48
	v_exp_f32_e32 v2, v2
	v_sub_f32_e32 v4, v4, v48
	v_exp_f32_e32 v3, v3
	v_sub_f32_e32 v5, v5, v48
	v_mul_f32_e32 v32, 0, v16
	v_exp_f32_e32 v4, v4
	v_sub_f32_e32 v6, v6, v48
	v_add_f32_e32 v16, v1, v0
	v_exp_f32_e32 v5, v5
	v_sub_f32_e32 v7, v7, v48
	v_add_f32_e32 v16, v2, v16
	v_exp_f32_e32 v6, v6
	v_sub_f32_e32 v8, v8, v48
	v_add_f32_e32 v16, v3, v16
	v_exp_f32_e32 v7, v7
	v_sub_f32_e32 v9, v9, v48
	v_add_f32_e32 v16, v4, v16
	v_exp_f32_e32 v8, v8
	v_sub_f32_e32 v10, v10, v48
	v_add_f32_e32 v16, v5, v16
	v_exp_f32_e32 v9, v9
	v_sub_f32_e32 v11, v11, v48
	v_add_f32_e32 v16, v6, v16
	v_exp_f32_e32 v10, v10
	v_sub_f32_e32 v12, v12, v48
	v_add_f32_e32 v16, v7, v16
	v_exp_f32_e32 v11, v11
	v_sub_f32_e32 v13, v13, v48
	v_add_f32_e32 v16, v8, v16
	v_exp_f32_e32 v12, v12
	v_sub_f32_e32 v14, v14, v48
	v_add_f32_e32 v16, v9, v16
	v_exp_f32_e32 v13, v13
	v_sub_f32_e32 v15, v15, v48
	v_add_f32_e32 v16, v10, v16
	v_exp_f32_e32 v14, v14
	v_add_f32_e32 v16, v11, v16
	v_exp_f32_e32 v15, v15
	v_add_f32_e32 v16, v12, v16
	v_add_f32_e32 v16, v13, v16
	v_add_f32_e32 v16, v14, v16
	v_add_u32_e32 v24, v119, v115
	v_add_f32_e32 v107, v15, v16
	ds_read_b64_tr_b16 v[16:17], v24 offset:13312
	ds_read_b64_tr_b16 v[18:19], v24 offset:14848
	ds_read_b64_tr_b16 v[20:21], v24 offset:16384
	ds_read_b64_tr_b16 v[22:23], v24 offset:17920
	s_movk_i32 s60, 0xc0
	v_mov_b32_e32 v33, v32
	v_mov_b32_e32 v34, v32
	v_mov_b32_e32 v35, v32
	v_mov_b32_e32 v36, v32
	v_mov_b32_e32 v37, v32
	v_mov_b32_e32 v38, v32
	v_mov_b32_e32 v39, v32
	v_mov_b32_e32 v40, v32
	v_mov_b32_e32 v41, v32
	v_mov_b32_e32 v42, v32
	v_mov_b32_e32 v43, v32
	v_mov_b32_e32 v44, v32
	v_mov_b32_e32 v45, v32
	v_mov_b32_e32 v46, v32
	v_mov_b32_e32 v47, v32
	v_cvt_pk_bf16_f32 v52, v0, v1
	v_cvt_pk_bf16_f32 v56, v8, v9
	v_cvt_pk_bf16_f32 v53, v2, v3
	v_cvt_pk_bf16_f32 v57, v10, v11
	v_cvt_pk_bf16_f32 v54, v4, v5
	v_cvt_pk_bf16_f32 v58, v12, v13
	v_cvt_pk_bf16_f32 v55, v6, v7
	v_cvt_pk_bf16_f32 v59, v14, v15
	s_setprio 1
	s_waitcnt lgkmcnt(2)
	v_mfma_f32_32x32x16_bf16 v[0:15], v[16:19], v[52:55], v[32:47]
	s_waitcnt lgkmcnt(0)
	v_mfma_f32_32x32x16_bf16 v[0:15], v[20:23], v[56:59], v[0:15]
	s_setprio 0
	ds_read_b64_tr_b16 v[60:61], v24 offset:13376
	ds_read_b64_tr_b16 v[62:63], v24 offset:14912
	ds_read_b64_tr_b16 v[120:121], v24 offset:16448
	ds_read_b64_tr_b16 v[122:123], v24 offset:17984
	s_setprio 1
	v_mov_b64_e32 v[16:17], v[32:33]
	v_mov_b64_e32 v[18:19], v[34:35]
	v_mov_b64_e32 v[20:21], v[36:37]
	v_mov_b64_e32 v[22:23], v[38:39]
	v_mov_b64_e32 v[24:25], v[40:41]
	v_mov_b64_e32 v[26:27], v[42:43]
	v_mov_b64_e32 v[28:29], v[44:45]
	v_mov_b64_e32 v[30:31], v[46:47]
	s_waitcnt lgkmcnt(2)
	s_nop 0
	v_mfma_f32_32x32x16_bf16 v[16:31], v[60:63], v[52:55], v[16:31]
	s_waitcnt lgkmcnt(0)
	v_mfma_f32_32x32x16_bf16 v[16:31], v[120:123], v[56:59], v[16:31]
	s_setprio 0
	v_mov_b32_e32 v49, v32
	v_mov_b32_e32 v106, v65
	v_add_f32_e64 v106, v48, v106
	v_add_f32_e64 v107, v49, v107
	v_xor_b32_e32 v32, 0x80000000, v106
	v_mov_b32_e32 v33, v32
	v_mov_b32_e32 v34, v32
	v_mov_b32_e32 v35, v32
	v_mov_b32_e32 v36, v32
	v_mov_b32_e32 v37, v32
	v_mov_b32_e32 v38, v32
	v_mov_b32_e32 v39, v32
	v_mov_b32_e32 v40, v32
	v_mov_b32_e32 v41, v32
	v_mov_b32_e32 v42, v32
	v_mov_b32_e32 v43, v32
	v_mov_b32_e32 v44, v32
	v_mov_b32_e32 v45, v32
	v_mov_b32_e32 v46, v32
	v_mov_b32_e32 v47, v32
	s_branch .LBB0_1089

; __device__ __forceinline__ unsigned cvt_pk_bf16(float lo, float hi) { const f32x2c_ v = {lo, hi}; const bf16x2c_ b = __builtin_convertvector(v, bf16x2c_); return __builtin_bit_cast(unsigned, b); }
; #define LAS __attribute__((address_space(3)))
; #define MFMA32(a, b, c) __builtin_amdgcn_mfma_f32_32x32x16_bf16(a, b, c, 0, 0, 0)
; __device__ __forceinline__ void attn_unit(int bh, int qb, const bf16_t* QKV, const bf16_t* KF, const float* cstab, const float* qg, bf16_t* MIX, LAS unsigned char* lds) {
;     ...
;             float ps = 0.f;
; #pragma unroll
;             for (int r = 0; r < 16; ++r) { p[r] = __builtin_amdgcn_exp2f(p[r]); ps += p[r]; }
;             lrun += ps;
;             u32x4 w0, w1;
; #pragma unroll
;             for (int k = 0; k < 4; ++k) { w0[k] = cvt_pk_bf16(p[2 * k], p[2 * k + 1]); w1[k] = cvt_pk_bf16(p[8 + 2 * k], p[8 + 2 * k + 1]); }
;             const bf16x8 pb0 = __builtin_bit_cast(bf16x8, w0), pb1 = __builtin_bit_cast(bf16x8, w1);
;             const LAS unsigned char* vp = buf + vtb + (32 * kb) * VROW;
; #pragma unroll
;             for (int db = 0; db < 2; ++db) {
;                 const v4i16_t a0 = __builtin_amdgcn_ds_read_tr16_b64_v4i16((LAS v4i16_t*)(vp + db * 64));
;                 const v4i16_t a1 = __builtin_amdgcn_ds_read_tr16_b64_v4i16((LAS v4i16_t*)(vp + db * 64 + 8 * VROW));
;                 const v4i16_t c0 = __builtin_amdgcn_ds_read_tr16_b64_v4i16((LAS v4i16_t*)(vp + db * 64 + 16 * VROW));
;                 const v4i16_t c1 = __builtin_amdgcn_ds_read_tr16_b64_v4i16((LAS v4i16_t*)(vp + db * 64 + 24 * VROW));
;                 const bf16x8 va = {a0[0], a0[1], a0[2], a0[3], a1[0], a1[1], a1[2], a1[3]}, vc = {c0[0], c0[1], c0[2], c0[3], c1[0], c1[1], c1[2], c1[3]};
;                 __builtin_amdgcn_s_setprio(1);
;                 if (db == 0) { o0 = MFMA32(va, pb0, o0); o0 = MFMA32(vc, pb1, o0); }
;                 else { o1 = MFMA32(va, pb0, o1); o1 = MFMA32(vc, pb1, o1); }
.LBB0_1107:
	v_exp_f32_e32 v48, v48
	v_exp_f32_e32 v49, v49
	v_exp_f32_e32 v50, v50
	v_exp_f32_e32 v51, v51
	v_exp_f32_e32 v122, v52
	v_add_f32_e32 v121, v49, v48
	v_add_f32_e32 v121, v50, v121
	v_add_f32_e32 v121, v51, v121
	v_add_f32_e32 v52, v122, v121
	v_exp_f32_e32 v121, v53
	v_exp_f32_e32 v123, v54
	v_exp_f32_e32 v55, v55
	v_exp_f32_e32 v53, v56
	v_add_f32_e32 v52, v121, v52
	v_exp_f32_e32 v54, v57
	v_add_f32_e32 v52, v123, v52
	v_exp_f32_e32 v56, v58
	v_add_f32_e32 v52, v55, v52
	v_exp_f32_e32 v57, v59
	v_add_f32_e32 v52, v53, v52
	v_exp_f32_e32 v58, v60
	v_add_f32_e32 v52, v54, v52
	v_exp_f32_e32 v59, v61
	v_add_f32_e32 v52, v56, v52
	v_exp_f32_e32 v60, v62
	v_add_f32_e32 v52, v57, v52
	v_exp_f32_e32 v61, v63
	v_add_f32_e32 v52, v58, v52
	v_add_f32_e32 v52, v59, v52
	v_add_f32_e32 v52, v60, v52
	v_cvt_pk_bf16_f32 v48, v48, v49
	v_cvt_pk_bf16_f32 v49, v50, v51
	v_cvt_pk_bf16_f32 v50, v122, v121
	v_add_u32_e32 v121, v119, v115
	v_add_f32_e32 v124, v61, v52
	v_cvt_pk_bf16_f32 v52, v53, v54
	v_cvt_pk_bf16_f32 v53, v56, v57
	v_cvt_pk_bf16_f32 v54, v58, v59
	v_cvt_pk_bf16_f32 v51, v123, v55
	v_cvt_pk_bf16_f32 v55, v60, v61
	ds_read_b64_tr_b16 v[56:57], v121 offset:13312
	ds_read_b64_tr_b16 v[58:59], v121 offset:14848
	ds_read_b64_tr_b16 v[60:61], v121 offset:16384
	ds_read_b64_tr_b16 v[62:63], v121 offset:17920
	s_setprio 1
	s_waitcnt lgkmcnt(2)
	v_mfma_f32_32x32x16_bf16 v[0:15], v[56:59], v[48:51], v[0:15]
	s_waitcnt lgkmcnt(0)
	v_mfma_f32_32x32x16_bf16 v[0:15], v[60:63], v[52:55], v[0:15]
	s_setprio 0
	ds_read_b64_tr_b16 v[56:57], v121 offset:13376
	ds_read_b64_tr_b16 v[58:59], v121 offset:14912
	ds_read_b64_tr_b16 v[60:61], v121 offset:16448
	ds_read_b64_tr_b16 v[62:63], v121 offset:17984
	s_setprio 1
	s_waitcnt lgkmcnt(2)
	v_mfma_f32_32x32x16_bf16 v[16:31], v[56:59], v[48:51], v[16:31]
	s_waitcnt lgkmcnt(0)
	v_mfma_f32_32x32x16_bf16 v[16:31], v[60:63], v[52:55], v[16:31]
	s_setprio 0
	v_add_f32_e32 v107, v107, v124
	s_add_i32 s30, s29, 0x60
	s_cmp_gt_i32 s30, s18
	s_cbranch_scc0 .LBB0_1110
